# P4 block-index remap: CU partners of prompt-scan blocks idle, other 256 blocks take all transposes
# speedup vs baseline: 1.0059x; 1.0059x over previous
.LBB0_1148:
	v_readlane_b32 s84, v245, 0
	v_readlane_b32 s87, v245, 9
	s_nop 3
	v_writelane_b32 v244, s84, 60
	v_writelane_b32 v244, s87, 61
	s_cmpk_lg_u32 s87, 0x200
	s_cbranch_scc1 .Lp4r_go
	s_sub_u32 s85, s84, 0x100
	s_cmpk_lt_u32 s85, 0x80
	s_cbranch_scc1 .LBB0_1545
	s_cmpk_ge_u32 s84, 0x180
	s_cselect_b32 s85, 0x80, 0
	s_sub_u32 s85, s84, s85
	s_movk_i32 s86, 0x180
	s_nop 0
	v_writelane_b32 v245, s85, 0
	v_writelane_b32 v245, s86, 9
	s_nop 1

.Lp4r_end:
	v_readlane_b32 s84, v244, 60
	v_readlane_b32 s85, v244, 61
	s_nop 3
	v_writelane_b32 v245, s84, 0
	v_writelane_b32 v245, s85, 9
	s_nop 1
